# P6 GEMM: slot->unit permutation so the heavy-epilogue N-tiles (k_rope scatter, ssq atomics) run on single-unit slots (store drain overlaps other slots' second unit)
# speedup vs baseline: 1.0040x; 1.0040x over previous
; #define GAS __attribute__((address_space(1)))
;     ...
;     const int nx = (gridDim.x == 256) ? 8 : 1, xcd = blockIdx.x % nx, nslots = gridDim.x / nx;
;     const int nloc = ((Mtiles - xcd + nx - 1) / nx) * Ntiles;
;     int u = blockIdx.x / nx;
;     const GAS bf16_t* Ag = (const GAS bf16_t*)A + dsrc;
;     const GAS bf16_t* Wg = (const GAS bf16_t*)Wt + dsrc;
;     if (u < nloc) {
;         Ag = (const GAS bf16_t*)(A + (size_t)(xcd + nx * (u / Ntiles)) * RM * K) + dsrc; Wg = (const GAS bf16_t*)(Wt + (size_t)(u % Ntiles) * 256 * K) + dsrc;
;         G_DMA(0, 0);
;     }
.LBB0_729:
	s_cmp_lt_i32 s24, 7
	s_cselect_b64 s[14:15], -1, 0
	s_and_b64 s[0:1], s[14:15], s[4:5]
	s_andn2_b64 vcc, exec, s[0:1]
	s_mov_b32 s3, 1
	s_cbranch_vccnz .LBB0_921
	s_mov_b64 s[0:1], s[28:29]
	s_mov_b64 s[6:7], s[30:31]
	s_cmp_lt_i32 s3, 1
	s_cbranch_scc1 .LBB0_921
	s_add_u32 s16, s6, 0x5158000
	s_addc_u32 s17, s7, 0
	s_add_u32 s20, s6, 0x5998000
	s_addc_u32 s21, s7, 0
	s_add_u32 s22, s6, 0xf0bc000
	s_addc_u32 s23, s7, 0
	s_add_u32 s24, s6, 0x8db8000
	s_addc_u32 s25, s7, 0
	s_add_u32 s8, s6, 0x16000
	s_addc_u32 s9, s7, 0
	s_waitcnt lgkmcnt(0)
	s_add_u32 s36, s6, 0x3058000
	s_addc_u32 s37, s7, 0
	s_load_dword s0, s[72:73], 0xb8
	s_add_u32 s38, s6, 0xf58000
	s_addc_u32 s39, s7, 0
	s_add_u32 s40, s6, 0x718000
	s_addc_u32 s41, s7, 0
	s_waitcnt lgkmcnt(0)
	s_cmpk_eq_i32 s0, 0x100
	s_cselect_b32 s1, 8, 1
	s_cselect_b32 s67, 3, 0
	s_add_i32 s4, s1, -1
	s_and_b32 s70, s4, s2
	s_lshr_b32 s71, s0, s67
	s_sub_i32 s0, s1, s70
	v_bfe_u32 v3, v202, 5, 1
	v_lshrrev_b32_e32 v0, 1, v202
	s_addk_i32 s0, 0x41
	v_bfe_u32 v4, v202, 1, 3
	v_bitop3_b32 v0, v3, v0, 7 bitop3:0x78
	s_lshr_b32 s72, s0, s67
	v_lshlrev_b32_e32 v176, 4, v0
	v_bitop3_b32 v0, v3, v4, 2 bitop3:0x36
	s_mul_i32 s72, s72, 6
	s_lshr_b32 s73, s2, s67
	v_lshlrev_b32_e32 v177, 4, v0
	v_bitop3_b32 v0, v3, v4, 4 bitop3:0x36
	s_mov_b32 s101, s73
	s_cmp_lg_u32 s71, 32
	s_cbranch_scc1 .Lp6mf_done
	s_sub_i32 s98, s72, 32
	s_cmp_lt_i32 s98, 1
	s_cbranch_scc1 .Lp6mf_done
	s_mul_hi_u32 s99, s72, 0x2aaaaaab
	s_cmp_lt_u32 s73, s98
	s_cbranch_scc1 .Lp6mf_d1
	s_cmp_lt_u32 s73, 32
	s_cbranch_scc0 .Lp6mf_d2
	s_sub_i32 s100, s73, s98
	s_branch .Lp6mf_heavy
.Lp6mf_d2:
	s_sub_i32 s100, s73, 32
	s_add_i32 s100, s100, s98
	s_branch .Lp6mf_q
.Lp6mf_d1:
	s_mov_b32 s100, s73
.Lp6mf_q:
	s_lshl_b32 s101, s99, 2
	s_cmp_lt_u32 s100, s101
	s_cbranch_scc0 .Lp6mf_left
	s_lshr_b32 s101, s100, 2
	s_mul_i32 s101, s101, 6
	s_and_b32 s100, s100, 3
	s_add_i32 s101, s101, s100
	s_add_i32 s101, s101, 2
	s_branch .Lp6mf_done
.Lp6mf_left:
	s_sub_i32 s100, s100, s101
	s_sub_i32 s101, 32, s98
	s_add_i32 s100, s100, s101
.Lp6mf_heavy:
	s_cmp_lt_u32 s100, s99
	s_cbranch_scc0 .Lp6mf_h0
	s_mul_i32 s101, s100, 6
	s_add_i32 s101, s101, 1
	s_branch .Lp6mf_done
.Lp6mf_h0:
	s_sub_i32 s100, s100, s99
	s_mul_i32 s101, s100, 6
.Lp6mf_done:
	s_cmp_lt_i32 s73, s72
	s_mul_hi_i32 s0, s101, 0x2aaaaaab
	v_lshlrev_b32_e32 v178, 4, v0
	v_bitop3_b32 v0, v3, v4, 6 bitop3:0x36
	s_cselect_b64 s[42:43], -1, 0
	s_lshr_b32 s1, s0, 31
	v_lshrrev_b32_e32 v155, 6, v202
	v_lshlrev_b32_e32 v179, 4, v0
	v_bfe_u32 v0, v202, 3, 3
	s_add_i32 s4, s0, s1
	v_lshl_or_b32 v0, v155, 3, v0
	s_lshl_b32 s0, s4, s67
	v_lshrrev_b32_e32 v5, 1, v0
	s_add_i32 s0, s0, s70
	v_xor_b32_e32 v5, v5, v202
	s_ashr_i32 s1, s0, 31
	v_lshlrev_b32_e32 v0, 10, v0
	v_lshlrev_b32_e32 v5, 3, v5
	s_lshl_b64 s[0:1], s[0:1], 19
	v_and_or_b32 v0, v5, 56, v0
	s_add_u32 s0, s38, s0
	v_mov_b32_e32 v133, 0
	v_lshlrev_b32_e32 v132, 1, v0
	s_addc_u32 s1, s39, s1
	s_mul_i32 s4, s4, 6
	v_lshl_add_u64 v[138:139], s[0:1], 0, v[132:133]
	s_sub_i32 s0, s101, s4
	s_ashr_i32 s1, s0, 31
	s_lshl_b64 s[0:1], s[0:1], 19
	s_add_u32 s0, s40, s0
	v_bfe_u32 v2, v202, 6, 2
	v_lshrrev_b32_e32 v4, 8, v202
	v_and_b32_e32 v180, 31, v202
	s_addc_u32 s1, s41, s1
	v_lshl_add_u64 v[140:141], s[0:1], 0, v[132:133]
	v_lshlrev_b32_e32 v181, 14, v4
	v_lshlrev_b32_e32 v182, 7, v180
	v_lshlrev_b32_e32 v183, 13, v2
	v_lshlrev_b32_e32 v184, 6, v2
	v_lshlrev_b32_e32 v154, 3, v3
	v_lshlrev_b32_e32 v156, 4, v3
	s_add_i32 s0, 16, 0x10000
	v_lshlrev_b32_e32 v2, 6, v180
	v_mov_b32_e32 v3, v133
	v_lshl_add_u64 v[134:135], s[38:39], 0, v[132:133]
	v_lshl_add_u64 v[136:137], s[40:41], 0, v[132:133]
	v_add3_u32 v186, s0, v181, v182
	s_add_i32 s0, 16, 0x18000
	v_or_b32_e32 v188, 32, v180
	v_and_b32_e32 v132, 32, v202
	v_lshl_add_u64 v[2:3], s[8:9], 0, v[2:3]
	v_and_b32_e32 v1, 63, v202
	s_mov_b64 s[44:45], 0x20000
	s_mov_b64 s[46:47], 0x40000
	s_mov_b64 s[48:49], 0x60000
	v_lshl_add_u64 v[158:159], s[8:9], 0, v[132:133]
	v_lshl_add_u64 v[160:161], v[2:3], 0, v[132:133]
	s_add_u32 s50, s6, 0xf0cc800
	v_lshlrev_b32_e32 v132, 6, v188
	v_lshlrev_b32_e32 v164, 1, v0
	v_mbcnt_lo_u32_b32 v0, -1, 0
	s_mov_b32 s33, s96
	s_mov_b32 s66, 0
	v_lshl_add_u64 v[142:143], v[138:139], 0, s[44:45]
	v_lshl_add_u64 v[144:145], v[140:141], 0, s[44:45]
	v_lshl_add_u64 v[146:147], v[138:139], 0, s[46:47]
	v_lshl_add_u64 v[148:149], v[140:141], 0, s[46:47]
	v_lshl_add_u64 v[150:151], v[138:139], 0, s[48:49]
	v_lshl_add_u64 v[152:153], v[140:141], 0, s[48:49]
	v_lshlrev_b32_e32 v185, 7, v4
	v_mov_b32_e32 v157, v133
	v_cmp_gt_u32_e64 s[4:5], 32, v1
	v_add3_u32 v187, s0, v183, v182
	s_addc_u32 s51, s7, 0
	v_lshl_add_u64 v[162:163], v[158:159], 0, v[132:133]
	s_movk_i32 s74, 0x2000
	s_movk_i32 s75, 0x6000
	s_mov_b64 s[52:53], 0x80
	s_mov_b64 s[54:55], 0x20080
	s_mov_b64 s[56:57], 0x40080
	s_mov_b64 s[58:59], 0x60080
	s_movk_i32 s76, 0x17f
	s_movk_i32 s77, 0x19f
	s_movk_i32 s78, 0x5a0
	s_movk_i32 s79, 0xff
	s_movk_i32 s80, 0x3fff
	s_movk_i32 s81, 0x84
	s_mov_b32 s82, 0x318000
	s_mov_b32 s83, 0x630000
	s_mov_b32 s84, 0x948000
	s_mov_b32 s85, 0xc60000
	s_mov_b32 s86, 0xf78000
	s_mov_b32 s87, 0x1290000
	s_mov_b32 s88, 0x15a8000
	s_mov_b32 s89, 0x18c0000
	s_mov_b32 s90, 0x1bd8000
	s_mov_b32 s91, 0x1ef0000
	s_mov_b32 s92, 0x2208000
	s_mov_b32 s93, 0x2520000
	s_mov_b32 s94, 0x2838000
	s_mov_b32 s95, 0x2b50000
	s_mov_b32 s96, 0x2e68000
	v_cndmask_b32_e64 v189, 0, 1, s[42:43]
	v_mbcnt_hi_u32_b32 v190, -1, v0
	s_branch .LBB0_733

; #define MFMA(a, b, c) __builtin_amdgcn_mfma_f32_32x32x16_bf16((a), (b), (c), 0, 0, 0)
; #define G_BARRIER() { asm volatile("s_waitcnt vmcnt(0) lgkmcnt(0)" ::: "memory"); __builtin_amdgcn_s_barrier(); asm volatile("" ::: "memory"); }
;     ...
;         for (int kt = 0; kt < nk; ++kt) {
;             if (kt + 1 < nk) { G_DMA(kt + 1, (kt + 1) & 1); }
;             const unsigned char* sa = lds + (kt & 1) * 65536 + (wt * 32 * TB + r) * 128;
;             const unsigned char* sw = lds + (kt & 1) * 65536 + 32768 + (wf * 64 + r) * 128;
; #pragma unroll
;             for (int ks = 0; ks < 4; ++ks) {
;                 bf16x8 wfr[2], afr[TB];
; #pragma unroll
;                 for (int fb = 0; fb < 2; ++fb) wfr[fb] = *(const bf16x8*)(sw + fb * 4096 + koff[ks]);
; #pragma unroll
;                 for (int tb = 0; tb < TB; ++tb) afr[tb] = *(const bf16x8*)(sa + tb * 4096 + koff[ks]);
; #pragma unroll
;                 for (int fb = 0; fb < 2; ++fb)
; #pragma unroll
;                     for (int tb = 0; tb < TB; ++tb) acc[fb][tb] = MFMA(wfr[fb], afr[tb], acc[fb][tb]);
;             }
;             G_BARRIER();
;         }
.LBB0_743:
	s_add_i32 s8, s0, 0x10000
	s_and_b32 s9, s8, 0x10000
	s_add_i32 s9, s97, s9
	s_mov_b32 m0, s9
	s_nop 0
	global_load_lds_dwordx4 v240, s[56:57]
	s_add_i32 m0, s9, 0x8000
	s_nop 0
	global_load_lds_dwordx4 v240, s[58:59]
	s_add_i32 m0, s9, 0x2000
	s_nop 0
	global_load_lds_dwordx4 v241, s[56:57]
	s_add_i32 m0, s9, 0xa000
	s_nop 0
	global_load_lds_dwordx4 v241, s[58:59]
	s_add_i32 m0, s9, 0x4000
	s_nop 0
	global_load_lds_dwordx4 v242, s[56:57]
	s_add_i32 m0, s9, 0xc000
	s_nop 0
	global_load_lds_dwordx4 v242, s[58:59]
	s_add_i32 m0, s9, 0x6000
	s_nop 0
	global_load_lds_dwordx4 v243, s[56:57]
	s_add_i32 m0, s9, 0xe000
	s_and_b32 s0, s0, 0x10000
	s_nop 0
	global_load_lds_dwordx4 v243, s[58:59]
	s_add_u32 s56, s56, 0x80
	s_addc_u32 s57, s57, 0
	s_add_u32 s58, s58, 0x80
	s_addc_u32 s59, s59, 0
	s_add_i32 s0, s0, 16
	v_add3_u32 v132, s0, v181, v182
	v_add3_u32 v165, s0, v183, v182
	v_add_u32_e32 v191, v165, v176
	v_add_u32_e32 v200, v132, v176
	ds_read_b128 v[128:131], v191 offset:32768
	ds_read_b128 v[170:173], v200
	ds_read_b128 v[192:195], v191 offset:36864
	ds_read_b128 v[196:199], v200 offset:4096
	ds_read_b128 v[204:207], v200 offset:8192
	ds_read_b128 v[208:211], v200 offset:12288
	v_add_u32_e32 v174, v165, v177
	v_add_u32_e32 v175, v132, v177
	ds_read_b128 v[216:219], v174 offset:32768
	ds_read_b128 v[220:223], v175
	ds_read_b128 v[224:227], v174 offset:36864
	ds_read_b128 v[228:231], v175 offset:4096
	ds_read_b128 v[232:235], v175 offset:8192
	ds_read_b128 v[236:239], v175 offset:12288
	s_waitcnt lgkmcnt(6)
	v_mfma_f32_32x32x16_bf16 v[112:127], v[128:131], v[170:173], v[112:127]
	s_add_u32 s6, s6, 0x80
	s_addc_u32 s7, s7, 0
	s_cmpk_eq_i32 s6, 0x780
	s_mov_b32 s0, s8
	v_mfma_f32_32x32x16_bf16 v[96:111], v[128:131], v[196:199], v[96:111]
	v_mfma_f32_32x32x16_bf16 v[80:95], v[128:131], v[204:207], v[80:95]
	v_mfma_f32_32x32x16_bf16 v[64:79], v[128:131], v[208:211], v[64:79]
	v_mfma_f32_32x32x16_bf16 v[48:63], v[192:195], v[170:173], v[48:63]
	v_mfma_f32_32x32x16_bf16 v[32:47], v[192:195], v[196:199], v[32:47]
	v_mfma_f32_32x32x16_bf16 v[16:31], v[192:195], v[204:207], v[16:31]
	v_mfma_f32_32x32x16_bf16 v[0:15], v[192:195], v[208:211], v[0:15]
	v_add_u32_e32 v174, v165, v178
	v_add_u32_e32 v175, v132, v178
	ds_read_b128 v[128:131], v174 offset:32768
	ds_read_b128 v[170:173], v175
	ds_read_b128 v[192:195], v174 offset:36864
	ds_read_b128 v[196:199], v175 offset:4096
	ds_read_b128 v[204:207], v175 offset:8192
	ds_read_b128 v[208:211], v175 offset:12288
	s_waitcnt lgkmcnt(6)
	v_mfma_f32_32x32x16_bf16 v[112:127], v[216:219], v[220:223], v[112:127]
	v_mfma_f32_32x32x16_bf16 v[96:111], v[216:219], v[228:231], v[96:111]
	v_mfma_f32_32x32x16_bf16 v[80:95], v[216:219], v[232:235], v[80:95]
	v_mfma_f32_32x32x16_bf16 v[64:79], v[216:219], v[236:239], v[64:79]
	v_mfma_f32_32x32x16_bf16 v[48:63], v[224:227], v[220:223], v[48:63]
	v_mfma_f32_32x32x16_bf16 v[32:47], v[224:227], v[228:231], v[32:47]
	v_mfma_f32_32x32x16_bf16 v[16:31], v[224:227], v[232:235], v[16:31]
	v_mfma_f32_32x32x16_bf16 v[0:15], v[224:227], v[236:239], v[0:15]
	v_add_u32_e32 v165, v165, v179
	v_add_u32_e32 v132, v132, v179
	ds_read_b128 v[216:219], v165 offset:32768
	ds_read_b128 v[220:223], v132
	ds_read_b128 v[224:227], v165 offset:36864
	ds_read_b128 v[228:231], v132 offset:4096
	ds_read_b128 v[232:235], v132 offset:8192
	ds_read_b128 v[236:239], v132 offset:12288
	s_waitcnt lgkmcnt(6)
	v_mfma_f32_32x32x16_bf16 v[112:127], v[128:131], v[170:173], v[112:127]
	v_mfma_f32_32x32x16_bf16 v[96:111], v[128:131], v[196:199], v[96:111]
	v_mfma_f32_32x32x16_bf16 v[80:95], v[128:131], v[204:207], v[80:95]
	v_mfma_f32_32x32x16_bf16 v[64:79], v[128:131], v[208:211], v[64:79]
	v_mfma_f32_32x32x16_bf16 v[48:63], v[192:195], v[170:173], v[48:63]
	v_mfma_f32_32x32x16_bf16 v[32:47], v[192:195], v[196:199], v[32:47]
	v_mfma_f32_32x32x16_bf16 v[16:31], v[192:195], v[204:207], v[16:31]
	v_mfma_f32_32x32x16_bf16 v[0:15], v[192:195], v[208:211], v[0:15]
	s_waitcnt vmcnt(0) lgkmcnt(0)
	s_barrier
	v_mfma_f32_32x32x16_bf16 v[112:127], v[216:219], v[220:223], v[112:127]
	v_mfma_f32_32x32x16_bf16 v[96:111], v[216:219], v[228:231], v[96:111]
	v_mfma_f32_32x32x16_bf16 v[80:95], v[216:219], v[232:235], v[80:95]
	v_mfma_f32_32x32x16_bf16 v[64:79], v[216:219], v[236:239], v[64:79]
	v_mfma_f32_32x32x16_bf16 v[48:63], v[224:227], v[220:223], v[48:63]
	v_mfma_f32_32x32x16_bf16 v[32:47], v[224:227], v[228:231], v[32:47]
	v_mfma_f32_32x32x16_bf16 v[16:31], v[224:227], v[232:235], v[16:31]
	v_mfma_f32_32x32x16_bf16 v[0:15], v[224:227], v[236:239], v[0:15]
	s_cbranch_scc0 .LBB0_743
; #define GAS __attribute__((address_space(1)))
; #define MFMA(a, b, c) __builtin_amdgcn_mfma_f32_32x32x16_bf16((a), (b), (c), 0, 0, 0)
; #define G_BARRIER() { asm volatile("s_waitcnt vmcnt(0) lgkmcnt(0)" ::: "memory"); __builtin_amdgcn_s_barrier(); asm volatile("" ::: "memory"); }
;     ...
;         for (int kt = 0; kt < nk; ++kt) {
;             if (kt + 1 < nk) { G_DMA(kt + 1, (kt + 1) & 1); }
;             const unsigned char* sa = lds + (kt & 1) * 65536 + (wt * 32 * TB + r) * 128;
;             const unsigned char* sw = lds + (kt & 1) * 65536 + 32768 + (wf * 64 + r) * 128;
; #pragma unroll
;             for (int ks = 0; ks < 4; ++ks) {
;                 bf16x8 wfr[2], afr[TB];
; #pragma unroll
;                 for (int fb = 0; fb < 2; ++fb) wfr[fb] = *(const bf16x8*)(sw + fb * 4096 + koff[ks]);
; #pragma unroll
;                 for (int tb = 0; tb < TB; ++tb) afr[tb] = *(const bf16x8*)(sa + tb * 4096 + koff[ks]);
; #pragma unroll
;                 for (int fb = 0; fb < 2; ++fb)
; #pragma unroll
;                     for (int tb = 0; tb < TB; ++tb) acc[fb][tb] = MFMA(wfr[fb], afr[tb], acc[fb][tb]);
;             }
;             G_BARRIER();
;         }
;         const int un = u + nslots;
;         if (un < nloc) {
;             Ag = (const GAS bf16_t*)(A + (size_t)(xcd + nx * (un / Ntiles)) * RM * K) + dsrc; Wg = (const GAS bf16_t*)(Wt + (size_t)(un % Ntiles) * 256 * K) + dsrc;
;             G_DMA(0, 0);
	v_add_u32_e32 v132, v187, v176
	ds_read_b128 v[128:131], v132
	v_add_u32_e32 v165, v186, v176
	ds_read_b128 v[170:173], v165
	ds_read_b128 v[192:195], v165 offset:4096
	ds_read_b128 v[196:199], v165 offset:8192
	ds_read_b128 v[204:207], v165 offset:12288
	v_add_u32_e32 v165, v186, v177
	s_add_i32 s0, s1, s71
	s_cmp_ge_i32 s0, s72
	s_waitcnt lgkmcnt(0)
	v_mfma_f32_32x32x16_bf16 v[112:127], v[128:131], v[170:173], v[112:127]
	s_cselect_b64 s[60:61], -1, 0
	s_cmp_lt_i32 s0, s72
	v_mfma_f32_32x32x16_bf16 v[96:111], v[128:131], v[192:195], v[96:111]
	v_mfma_f32_32x32x16_bf16 v[80:95], v[128:131], v[196:199], v[80:95]
	v_mfma_f32_32x32x16_bf16 v[64:79], v[128:131], v[204:207], v[64:79]
	ds_read_b128 v[128:131], v132 offset:4096
	v_add_u32_e32 v132, v187, v177
	s_waitcnt lgkmcnt(0)
	v_mfma_f32_32x32x16_bf16 v[48:63], v[128:131], v[170:173], v[48:63]
	ds_read_b128 v[170:173], v165
	v_mfma_f32_32x32x16_bf16 v[32:47], v[128:131], v[192:195], v[32:47]
	ds_read_b128 v[192:195], v165 offset:4096
	v_mfma_f32_32x32x16_bf16 v[16:31], v[128:131], v[196:199], v[16:31]
	ds_read_b128 v[196:199], v165 offset:8192
	v_mfma_f32_32x32x16_bf16 v[0:15], v[128:131], v[204:207], v[0:15]
	ds_read_b128 v[128:131], v132
	ds_read_b128 v[204:207], v165 offset:12288
	v_add_u32_e32 v165, v186, v178
	s_waitcnt lgkmcnt(0)
	v_mfma_f32_32x32x16_bf16 v[112:127], v[128:131], v[170:173], v[112:127]
	v_mfma_f32_32x32x16_bf16 v[96:111], v[128:131], v[192:195], v[96:111]
	v_mfma_f32_32x32x16_bf16 v[80:95], v[128:131], v[196:199], v[80:95]
	v_mfma_f32_32x32x16_bf16 v[64:79], v[128:131], v[204:207], v[64:79]
	ds_read_b128 v[128:131], v132 offset:4096
	v_add_u32_e32 v132, v187, v178
	s_waitcnt lgkmcnt(0)
	v_mfma_f32_32x32x16_bf16 v[48:63], v[128:131], v[170:173], v[48:63]
	ds_read_b128 v[170:173], v165
	v_mfma_f32_32x32x16_bf16 v[32:47], v[128:131], v[192:195], v[32:47]
	ds_read_b128 v[192:195], v165 offset:4096
	v_mfma_f32_32x32x16_bf16 v[16:31], v[128:131], v[196:199], v[16:31]
	ds_read_b128 v[196:199], v165 offset:8192
	v_mfma_f32_32x32x16_bf16 v[0:15], v[128:131], v[204:207], v[0:15]
	ds_read_b128 v[128:131], v132
	ds_read_b128 v[204:207], v165 offset:12288
	v_add_u32_e32 v165, v186, v179
	s_waitcnt lgkmcnt(0)
	v_mfma_f32_32x32x16_bf16 v[112:127], v[128:131], v[170:173], v[112:127]
	v_mfma_f32_32x32x16_bf16 v[96:111], v[128:131], v[192:195], v[96:111]
	v_mfma_f32_32x32x16_bf16 v[80:95], v[128:131], v[196:199], v[80:95]
	v_mfma_f32_32x32x16_bf16 v[64:79], v[128:131], v[204:207], v[64:79]
	ds_read_b128 v[128:131], v132 offset:4096
	v_add_u32_e32 v132, v187, v179
	s_waitcnt lgkmcnt(0)
	v_mfma_f32_32x32x16_bf16 v[48:63], v[128:131], v[170:173], v[48:63]
	ds_read_b128 v[170:173], v165
	v_mfma_f32_32x32x16_bf16 v[32:47], v[128:131], v[192:195], v[32:47]
	ds_read_b128 v[192:195], v165 offset:4096
	v_mfma_f32_32x32x16_bf16 v[16:31], v[128:131], v[196:199], v[16:31]
	ds_read_b128 v[196:199], v165 offset:8192
	v_mfma_f32_32x32x16_bf16 v[0:15], v[128:131], v[204:207], v[0:15]
	ds_read_b128 v[128:131], v132
	ds_read_b128 v[204:207], v165 offset:12288
	s_waitcnt lgkmcnt(0)
	v_mfma_f32_32x32x16_bf16 v[112:127], v[128:131], v[170:173], v[112:127]
	v_mfma_f32_32x32x16_bf16 v[96:111], v[128:131], v[192:195], v[96:111]
	v_mfma_f32_32x32x16_bf16 v[80:95], v[128:131], v[196:199], v[80:95]
	v_mfma_f32_32x32x16_bf16 v[64:79], v[128:131], v[204:207], v[64:79]
	ds_read_b128 v[128:131], v132 offset:4096
	s_waitcnt vmcnt(0) lgkmcnt(0)
	s_barrier
	s_waitcnt lgkmcnt(0)
	v_mfma_f32_32x32x16_bf16 v[48:63], v[128:131], v[170:173], v[48:63]
	v_mfma_f32_32x32x16_bf16 v[32:47], v[128:131], v[192:195], v[32:47]
	v_mfma_f32_32x32x16_bf16 v[16:31], v[128:131], v[196:199], v[16:31]
	v_mfma_f32_32x32x16_bf16 v[0:15], v[128:131], v[204:207], v[0:15]
	s_cbranch_scc0 .LBB0_746
	s_mov_b32 s101, s0
	s_cmp_lg_u32 s71, 32
	s_cbranch_scc1 .Lp6mn_done
	s_sub_i32 s98, s72, 32
	s_cmp_lt_i32 s98, 1
	s_cbranch_scc1 .Lp6mn_done
	s_mul_hi_u32 s99, s72, 0x2aaaaaab
	s_cmp_lt_u32 s0, s98
	s_cbranch_scc1 .Lp6mn_d1
	s_cmp_lt_u32 s0, 32
	s_cbranch_scc0 .Lp6mn_d2
	s_sub_i32 s100, s0, s98
	s_branch .Lp6mn_heavy
.Lp6mn_d2:
	s_sub_i32 s100, s0, 32
	s_add_i32 s100, s100, s98
	s_branch .Lp6mn_q
.Lp6mn_d1:
	s_mov_b32 s100, s0

; #define GAS __attribute__((address_space(1)))
;     ...
;         const int un = u + nslots;
;         if (un < nloc) {
;             Ag = (const GAS bf16_t*)(A + (size_t)(xcd + nx * (un / Ntiles)) * RM * K) + dsrc; Wg = (const GAS bf16_t*)(Wt + (size_t)(un % Ntiles) * 256 * K) + dsrc;
;             G_DMA(0, 0);
;         }
.Lp6mn_done:
	s_mul_hi_i32 s6, s101, 0x2aaaaaab
	s_lshr_b32 s7, s6, 31
	s_add_i32 s8, s6, s7
	s_lshl_b32 s6, s8, s67
	s_add_i32 s6, s6, s70
	s_ashr_i32 s7, s6, 31
	s_lshl_b64 s[6:7], s[6:7], 19
	s_add_u32 s6, s38, s6
	s_mul_i32 s8, s8, 6
	s_addc_u32 s7, s39, s7
	s_sub_i32 s8, s101, s8
	s_ashr_i32 s9, s8, 31
	s_lshl_b64 s[8:9], s[8:9], 19
	s_mov_b32 m0, s97
	v_mov_b32_e32 v165, v133
	s_add_u32 s8, s40, s8
	v_lshl_add_u64 v[166:167], s[6:7], 0, v[164:165]
	s_addc_u32 s9, s41, s9
	global_load_lds_dwordx4 v164, s[6:7]
	s_add_i32 m0, s97, 0x8000
	v_lshl_add_u64 v[168:169], s[8:9], 0, v[164:165]
	global_load_lds_dwordx4 v164, s[8:9]
	v_lshl_add_u64 v[128:129], v[166:167], 0, s[44:45]
	s_add_i32 m0, s97, 0x2000
	s_nop 0
	global_load_lds_dwordx4 v[128:129], off
	v_lshl_add_u64 v[128:129], v[168:169], 0, s[44:45]
	s_add_i32 m0, s97, 0xa000
	s_nop 0
	global_load_lds_dwordx4 v[128:129], off
	v_lshl_add_u64 v[128:129], v[166:167], 0, s[46:47]
	s_add_i32 m0, s97, 0x4000
	s_nop 0
	global_load_lds_dwordx4 v[128:129], off
	v_lshl_add_u64 v[128:129], v[168:169], 0, s[46:47]
	s_add_i32 m0, s97, 0xc000
	s_nop 0
	global_load_lds_dwordx4 v[128:129], off
	v_lshl_add_u64 v[128:129], v[166:167], 0, s[48:49]
	s_add_i32 m0, s97, 0x6000
	s_nop 0
	global_load_lds_dwordx4 v[128:129], off
	v_lshl_add_u64 v[128:129], v[168:169], 0, s[48:49]
	s_add_i32 m0, s97, 0xe000
	s_nop 0
	global_load_lds_dwordx4 v[128:129], off
.LBB0_746:
	s_mov_b32 s101, s1
	s_cmp_lg_u32 s71, 32
	s_cbranch_scc1 .Lp6mc_done
	s_sub_i32 s98, s72, 32
	s_cmp_lt_i32 s98, 1
	s_cbranch_scc1 .Lp6mc_done
	s_mul_hi_u32 s99, s72, 0x2aaaaaab
	s_cmp_lt_u32 s1, s98
	s_cbranch_scc1 .Lp6mc_d1
	s_cmp_lt_u32 s1, 32
	s_cbranch_scc0 .Lp6mc_d2
	s_sub_i32 s100, s1, s98
	s_branch .Lp6mc_heavy
.Lp6mc_d2:
	s_sub_i32 s100, s1, 32
	s_add_i32 s100, s100, s98
	s_branch .Lp6mc_q
.Lp6mc_d1:
	s_mov_b32 s100, s1

; #define GAS __attribute__((address_space(1)))
; DI unsigned pk2(float a, float b) { f32x2 v = {a, b}; bf16x2_t r = __builtin_convertvector(v, bf16x2_t); return __builtin_bit_cast(unsigned, r); }
; DI float silu_f(float v) { return v * __builtin_amdgcn_rcpf(1.f + __builtin_amdgcn_exp2f(-1.4426950408889634f * v)); }
; DI void store_bf16_row32(bf16_t* rowp, const float (&v)[16], int hh) {
; #pragma unroll
;     for (int p = 0; p < 2; ++p) {
;         unsigned ax = pk2(v[8 * p + 0], v[8 * p + 1]), ay = pk2(v[8 * p + 2], v[8 * p + 3]);
;         unsigned bx = pk2(v[8 * p + 4], v[8 * p + 5]), by = pk2(v[8 * p + 6], v[8 * p + 7]);
;         const auto rx = __builtin_amdgcn_permlane32_swap(ax, bx, false, false);
;         const auto ry = __builtin_amdgcn_permlane32_swap(ay, by, false, false);
;         u32x4 w; w.x = rx[0]; w.y = ry[0]; w.z = rx[1]; w.w = ry[1];
;         *(GAS u32x4*)(rowp + 16 * p + 8 * hh) = w;
;     }
; }
;     DI void operator()(int fbase, int tbase, const f32x16& acc, int r, int hh) const {
;     ...
;         } else if (fbase < 1440) {
;             float o[16];
; #pragma unroll
;             for (int i = 0; i < 16; ++i) o[i] = silu_f(acc[i]);
;             store_bf16_row32(sg + (size_t)t * 1024 + (fbase - 416), o, hh);
.Lp6mc_done:
	s_mul_hi_i32 s6, s101, 0x2aaaaaab
	s_lshr_b32 s7, s6, 31
	s_add_i32 s6, s6, s7
	s_lshl_b32 s7, s6, s67
	s_mul_i32 s6, s6, 6
	s_add_i32 s7, s7, s70
	s_sub_i32 s1, s101, s6
	v_lshl_add_u32 v192, s7, 8, v185
	v_lshl_or_b32 v132, s1, 8, v184
	v_add_u32_e32 v128, 0xffffc000, v192
	v_lshrrev_b32_e32 v165, 8, v128
	v_ashrrev_i32_e32 v191, 13, v192
	v_cmp_lt_i32_e64 s[10:11], s76, v132
	v_cmp_lt_u32_e64 s[8:9], s77, v132
	v_cmp_gt_u32_e64 s[6:7], s78, v132
	v_cmp_lt_i32_e32 vcc, s79, v132
	v_or_b32_e32 v172, v192, v180
	s_and_saveexec_b64 s[12:13], s[10:11]
	s_xor_b64 s[62:63], exec, s[12:13]
	s_cbranch_execz .LBB0_758
	s_and_saveexec_b64 s[12:13], s[8:9]
	s_xor_b64 s[12:13], exec, s[12:13]
	s_cbranch_execz .LBB0_751
	s_and_saveexec_b64 s[18:19], s[6:7]
	s_cbranch_execz .LBB0_750
	v_mul_f32_e32 v128, 0xbfb8aa3b, v112
	v_mul_f32_e32 v129, 0xbfb8aa3b, v113
	v_exp_f32_e32 v128, v128
	v_exp_f32_e32 v129, v129
	v_mul_f32_e32 v130, 0xbfb8aa3b, v114
	v_mul_f32_e32 v131, 0xbfb8aa3b, v115
	v_add_f32_e32 v128, 1.0, v128
	v_add_f32_e32 v129, 1.0, v129
	v_rcp_f32_e32 v128, v128
	v_rcp_f32_e32 v129, v129
	v_exp_f32_e32 v130, v130
	v_exp_f32_e32 v131, v131
	v_mul_f32_e32 v173, 0xbfb8aa3b, v126
	v_pk_mul_f32 v[112:113], v[112:113], v[128:129]
	v_add_f32_e32 v128, 1.0, v130
	v_add_f32_e32 v129, 1.0, v131
	v_mul_f32_e32 v130, 0xbfb8aa3b, v116
	v_mul_f32_e32 v131, 0xbfb8aa3b, v117
	v_rcp_f32_e32 v128, v128
	v_rcp_f32_e32 v129, v129
	v_exp_f32_e32 v130, v130
	v_exp_f32_e32 v131, v131
	v_mul_f32_e32 v170, 0xbfb8aa3b, v124
	v_pk_mul_f32 v[114:115], v[114:115], v[128:129]
	v_add_f32_e32 v128, 1.0, v130
	v_add_f32_e32 v129, 1.0, v131
	v_mul_f32_e32 v130, 0xbfb8aa3b, v118
	v_mul_f32_e32 v131, 0xbfb8aa3b, v119
	v_rcp_f32_e32 v128, v128
	v_rcp_f32_e32 v129, v129
	v_exp_f32_e32 v130, v130
	v_exp_f32_e32 v131, v131
	v_mul_f32_e32 v171, 0xbfb8aa3b, v125
	v_pk_mul_f32 v[116:117], v[116:117], v[128:129]
	v_add_f32_e32 v128, 1.0, v130
	v_add_f32_e32 v129, 1.0, v131
	v_mul_f32_e32 v130, 0xbfb8aa3b, v120
	v_mul_f32_e32 v131, 0xbfb8aa3b, v121
	v_rcp_f32_e32 v128, v128
	v_rcp_f32_e32 v129, v129
	v_exp_f32_e32 v130, v130
	v_exp_f32_e32 v131, v131
	v_exp_f32_e32 v173, v173
	v_pk_mul_f32 v[118:119], v[118:119], v[128:129]
	v_add_f32_e32 v128, 1.0, v130
	v_add_f32_e32 v129, 1.0, v131
	v_mul_f32_e32 v130, 0xbfb8aa3b, v122
	v_mul_f32_e32 v131, 0xbfb8aa3b, v123
	v_exp_f32_e32 v130, v130
	v_exp_f32_e32 v131, v131
	v_mul_f32_e32 v174, 0xbfb8aa3b, v127
	v_exp_f32_e32 v170, v170
	v_exp_f32_e32 v171, v171
	v_exp_f32_e32 v175, v174
	v_rcp_f32_e32 v128, v128
	v_rcp_f32_e32 v129, v129
	v_add_f32_e32 v130, 1.0, v130
	v_add_f32_e32 v131, 1.0, v131
	v_add_f32_e32 v173, 1.0, v173
	v_rcp_f32_e32 v130, v130
	v_rcp_f32_e32 v131, v131
	v_add_f32_e32 v170, 1.0, v170
	v_add_f32_e32 v171, 1.0, v171
	v_rcp_f32_e32 v174, v173
	v_add_f32_e32 v173, 1.0, v175
	v_rcp_f32_e32 v170, v170
	v_rcp_f32_e32 v171, v171
	v_rcp_f32_e32 v175, v173
	v_ashrrev_i32_e32 v173, 31, v172
	v_pk_mul_f32 v[120:121], v[120:121], v[128:129]
	v_lshlrev_b64 v[128:129], 11, v[172:173]
	v_lshl_add_u64 v[128:129], s[36:37], 0, v[128:129]
	v_pk_mul_f32 v[122:123], v[122:123], v[130:131]
	v_lshl_add_u64 v[128:129], v[132:133], 1, v[128:129]
	v_lshlrev_b32_e32 v130, 1, v154
	v_mov_b32_e32 v131, v133
	v_cvt_pk_bf16_f32 v112, v112, v113
	v_cvt_pk_bf16_f32 v113, v114, v115
	v_cvt_pk_bf16_f32 v114, v116, v117
	v_cvt_pk_bf16_f32 v115, v118, v119
	v_pk_mul_f32 v[124:125], v[124:125], v[170:171]
	v_pk_mul_f32 v[126:127], v[126:127], v[174:175]
	v_lshl_add_u64 v[128:129], v[128:129], 0, v[130:131]
	v_permlane32_swap_b32_e32 v112, v114
	v_permlane32_swap_b32_e32 v113, v115
	global_store_dwordx4 v[128:129], v[112:115], off offset:-832
	s_nop 1
	v_cvt_pk_bf16_f32 v112, v120, v121
	v_cvt_pk_bf16_f32 v113, v122, v123
	v_cvt_pk_bf16_f32 v114, v124, v125
	v_cvt_pk_bf16_f32 v115, v126, v127
	s_nop 0
	v_permlane32_swap_b32_e32 v112, v114
	v_permlane32_swap_b32_e32 v113, v115
	global_store_dwordx4 v[128:129], v[112:115], off offset:-800

; #define LAS __attribute__((address_space(3)))
; extern "C" __global__ void __launch_bounds__(512) mega_fwd(Params p) {
;     extern __shared__ __attribute__((aligned(16))) unsigned char lds[];
;     const int tid = threadIdx.x;
;     __shared__ uint4 xb_words;
;     if (tid == 0) xb_words = make_uint4(0u, 0u, 0u, 0u);
;     __syncthreads();
;     XcdBarrier xb; xb.bar = (unsigned*)(p.ws + WS_BAR); xb.x = 0; xb.st = (volatile LAS unsigned*)&xb_words;
;     if (p.ph_hi - p.ph_lo > 1) xb = xcd_barrier_post((unsigned*)(p.ws + WS_BAR), (volatile LAS unsigned*)&xb_words);
;     if (p.ph_lo < 0) cg::this_grid().sync();
	.amdhsa_kernel mega_fwd
		.amdhsa_group_segment_fixed_size 16
		.amdhsa_private_segment_fixed_size 0
		.amdhsa_kernarg_size 440
		.amdhsa_user_sgpr_count 2
		.amdhsa_user_sgpr_dispatch_ptr 0
		.amdhsa_user_sgpr_queue_ptr 0
		.amdhsa_user_sgpr_kernarg_segment_ptr 1
		.amdhsa_user_sgpr_dispatch_id 0
		.amdhsa_user_sgpr_kernarg_preload_length 0
		.amdhsa_user_sgpr_kernarg_preload_offset 0
		.amdhsa_user_sgpr_private_segment_size 0
		.amdhsa_uses_dynamic_stack 0
		.amdhsa_enable_private_segment 0
		.amdhsa_system_sgpr_workgroup_id_x 1
		.amdhsa_system_sgpr_workgroup_id_y 0
		.amdhsa_system_sgpr_workgroup_id_z 0
		.amdhsa_system_sgpr_workgroup_info 0
		.amdhsa_system_vgpr_workitem_id 2
		.amdhsa_next_free_vgpr 248
		.amdhsa_next_free_sgpr 102
		.amdhsa_accum_offset 248
		.amdhsa_reserve_vcc 1
		.amdhsa_float_round_mode_32 0
		.amdhsa_float_round_mode_16_64 0
		.amdhsa_float_denorm_mode_32 3
		.amdhsa_float_denorm_mode_16_64 3
		.amdhsa_dx10_clamp 1
		.amdhsa_ieee_mode 1
		.amdhsa_fp16_overflow 0
		.amdhsa_tg_split 0
		.amdhsa_exception_fp_ieee_invalid_op 0
		.amdhsa_exception_fp_denorm_src 0
		.amdhsa_exception_fp_ieee_div_zero 0
		.amdhsa_exception_fp_ieee_overflow 0
		.amdhsa_exception_fp_ieee_underflow 0
		.amdhsa_exception_fp_ieee_inexact 0
		.amdhsa_exception_int_div_zero 0
	.end_amdhsa_kernel

; #define LAS __attribute__((address_space(3)))
; extern "C" __global__ void __launch_bounds__(512) mega_fwd(Params p) {
;     extern __shared__ __attribute__((aligned(16))) unsigned char lds[];
;     const int tid = threadIdx.x;
;     __shared__ uint4 xb_words;
;     if (tid == 0) xb_words = make_uint4(0u, 0u, 0u, 0u);
;     __syncthreads();
;     XcdBarrier xb; xb.bar = (unsigned*)(p.ws + WS_BAR); xb.x = 0; xb.st = (volatile LAS unsigned*)&xb_words;
;     if (p.ph_hi - p.ph_lo > 1) xb = xcd_barrier_post((unsigned*)(p.ws + WS_BAR), (volatile LAS unsigned*)&xb_words);
;     if (p.ph_lo < 0) cg::this_grid().sync();
amdhsa.kernels:
  - .agpr_count:     0
    .args:
      - .offset:         0
        .size:           184
        .value_kind:     by_value
      - .offset:         184
        .size:           4
        .value_kind:     hidden_block_count_x
      - .offset:         188
        .size:           4
        .value_kind:     hidden_block_count_y
      - .offset:         192
        .size:           4
        .value_kind:     hidden_block_count_z
      - .offset:         196
        .size:           2
        .value_kind:     hidden_group_size_x
      - .offset:         198
        .size:           2
        .value_kind:     hidden_group_size_y
      - .offset:         200
        .size:           2
        .value_kind:     hidden_group_size_z
      - .offset:         202
        .size:           2
        .value_kind:     hidden_remainder_x
      - .offset:         204
        .size:           2
        .value_kind:     hidden_remainder_y
      - .offset:         206
        .size:           2
        .value_kind:     hidden_remainder_z
      - .offset:         224
        .size:           8
        .value_kind:     hidden_global_offset_x
      - .offset:         232
        .size:           8
        .value_kind:     hidden_global_offset_y
      - .offset:         240
        .size:           8
        .value_kind:     hidden_global_offset_z
      - .offset:         248
        .size:           2
        .value_kind:     hidden_grid_dims
      - .offset:         272
        .size:           8
        .value_kind:     hidden_multigrid_sync_arg
      - .offset:         304
        .size:           4
        .value_kind:     hidden_dynamic_lds_size
    .group_segment_fixed_size: 16
    .kernarg_segment_align: 8
    .kernarg_segment_size: 440
    .language:       OpenCL C
    .language_version:
      - 2
      - 0
    .max_flat_workgroup_size: 512
    .name:           mega_fwd
    .private_segment_fixed_size: 0
    .sgpr_count:     108
    .sgpr_spill_count: 18
    .symbol:         mega_fwd.kd
    .uniform_work_group_size: 1
    .uses_dynamic_stack: false
    .vgpr_count:     248
    .vgpr_spill_count: 0
    .wavefront_size: 64
